# MoBA: computing waves do next-tile LDS write + global prefetch after the QK section instead of at interval head
# baseline (speedup 1.0000x reference)
.LBB0_148:
	s_cmp_ge_i32 s16, s48
	s_cselect_b64 s[8:9], -1, 0
	s_mov_b64 s[80:81], s[0:1]
	s_and_b64 vcc, exec, s[8:9]
	s_cbranch_vccnz .LBB0_151
	s_ashr_i32 s82, s51, 1
	s_sub_i32 s82, s47, s82
	s_lshl_b32 s82, 1, s82
	s_and_b32 s82, s82, s49
	s_cmp_lg_u32 s82, 0
	s_cbranch_scc1 .LBB0_151
	s_xor_b32 s10, s15, 1
	s_mul_i32 s10, s10, 0x11000
	s_add_i32 s10, s10, 0
	v_add3_u32 v85, s10, v165, v216
	v_add3_u32 v84, s10, v0, v216
	v_add_u32_e32 v86, 0x8800, v85
	s_waitcnt vmcnt(7)
	ds_write_b128 v84, v[4:7]
	s_waitcnt vmcnt(6)
	ds_write2_b64 v86, v[8:9], v[10:11] offset1:2
	s_waitcnt vmcnt(5)
	ds_write_b128 v84, v[12:15] offset:8704
	v_add_u32_e32 v86, 0xa800, v85
	s_waitcnt vmcnt(4)
	ds_write2_b64 v86, v[16:17], v[18:19] offset0:64 offset1:66
	s_waitcnt vmcnt(3)
	ds_write_b128 v84, v[20:23] offset:17408
	v_add_u32_e32 v86, 0xc800, v85
	s_waitcnt vmcnt(2)
	ds_write2_b64 v86, v[24:25], v[26:27] offset0:128 offset1:130
	s_waitcnt vmcnt(1)
	ds_write_b128 v84, v[28:31] offset:26112
	v_add_u32_e32 v84, 0xe800, v85
	s_andn2_b64 vcc, exec, s[0:1]
	s_waitcnt vmcnt(0)
	ds_write2_b64 v84, v[32:33], v[34:35] offset0:192 offset1:194
	s_cbranch_vccnz .LBB0_151
	s_lshr_b32 s0, s14, 1
	s_sub_i32 s0, s47, s0
	s_lshl_b32 s1, s14, 7
	s_lshl_b32 s0, s0, 8
	s_and_b32 s1, s1, 0x80
	s_or_b32 s0, s0, s1
	s_ashr_i32 s1, s0, 31
	v_lshl_add_u64 v[4:5], v[140:141], 0, s[0:1]
	v_mov_b64_e32 v[6:7], s[88:89]
	v_lshl_add_u64 v[28:29], s[0:1], 1, v[118:119]
	v_mad_u64_u32 v[6:7], s[0:1], v4, s72, v[6:7]
	v_mad_i32_i24 v7, v5, s72, v7
	v_lshl_add_u64 v[4:5], v[6:7], 0, s[20:21]
	v_lshl_add_u64 v[30:31], v[4:5], 0, v[2:3]
	v_add_co_u32_e32 v4, vcc, s3, v30
	s_mov_b32 s0, 0x3d000
	s_nop 0
	v_addc_co_u32_e32 v5, vcc, 0, v31, vcc
	v_add_co_u32_e32 v12, vcc, s0, v30
	v_lshl_add_u64 v[8:9], v[28:29], 0, v[146:147]
	s_nop 0
	v_addc_co_u32_e32 v13, vcc, 0, v31, vcc
	v_add_co_u32_e32 v20, vcc, 0x79000, v30
	v_lshl_add_u64 v[16:17], v[28:29], 0, v[148:149]
	s_nop 0
	v_addc_co_u32_e32 v21, vcc, 0, v31, vcc
	v_add_co_u32_e32 v30, vcc, 0xb5000, v30
	v_lshl_add_u64 v[24:25], v[28:29], 0, v[150:151]
	s_nop 0
	v_addc_co_u32_e32 v31, vcc, 0, v31, vcc
	v_lshl_add_u64 v[32:33], v[28:29], 0, v[152:153]
	global_load_dwordx4 v[4:7], v[4:5], off offset:1024
	s_nop 0
	global_load_dwordx4 v[8:11], v[8:9], off
	s_nop 0
	global_load_dwordx4 v[12:15], v[12:13], off offset:1024
	s_nop 0
	global_load_dwordx4 v[16:19], v[16:17], off
	s_nop 0
	global_load_dwordx4 v[20:23], v[20:21], off offset:1024
	s_nop 0
	global_load_dwordx4 v[24:27], v[24:25], off
	s_nop 0
	global_load_dwordx4 v[28:31], v[30:31], off offset:1024
	s_nop 0
	global_load_dwordx4 v[32:35], v[32:33], off
.LBB0_151:
	s_ashr_i32 s0, s51, 1
	s_sub_i32 s0, s47, s0
	s_lshl_b32 s0, 1, s0
	s_and_b32 s1, s0, s49
	s_cmp_eq_u32 s1, 0
	s_cbranch_scc1 .LBB0_137
	s_mul_i32 s1, s15, 0x11000
	s_add_i32 s1, s1, 0
	v_add_u32_e32 v84, s1, v167
	v_add_u32_e32 v195, v84, v158
	v_add3_u32 v197, s1, v158, v167
	ds_read_b128 v[84:87], v195
	ds_read_b128 v[88:91], v195 offset:64
	ds_read_b128 v[92:95], v195 offset:128
	ds_read_b128 v[96:99], v195 offset:192
	ds_read_b128 v[100:103], v197 offset:272
	ds_read_b128 v[104:107], v197 offset:336
	ds_read_b128 v[108:111], v197 offset:400
	ds_read_b128 v[198:201], v197 offset:464
	s_waitcnt lgkmcnt(4)
	v_mfma_f32_16x16x32_bf16 v[84:87], v[84:87], v[36:39], 0
	v_mfma_f32_16x16x32_bf16 v[84:87], v[88:91], v[40:43], v[84:87]
	v_mfma_f32_16x16x32_bf16 v[84:87], v[92:95], v[44:47], v[84:87]
	v_mfma_f32_16x16x32_bf16 v[112:115], v[96:99], v[48:51], v[84:87]
	s_nop 5
	ds_read_b128 v[84:87], v197 offset:8704
	ds_read_b128 v[88:91], v197 offset:8768
	ds_read_b128 v[92:95], v197 offset:8832
	ds_read_b128 v[96:99], v197 offset:8896
	s_waitcnt lgkmcnt(4)
	v_mfma_f32_16x16x32_bf16 v[100:103], v[100:103], v[36:39], 0
	v_mfma_f32_16x16x32_bf16 v[100:103], v[104:107], v[40:43], v[100:103]
	v_mfma_f32_16x16x32_bf16 v[100:103], v[108:111], v[44:47], v[100:103]
	v_mfma_f32_16x16x32_bf16 v[108:111], v[198:201], v[48:51], v[100:103]
	s_nop 5
	ds_read_b128 v[100:103], v197 offset:8976
	ds_read_b128 v[198:201], v197 offset:9040
	ds_read_b128 v[202:205], v197 offset:9104
	ds_read_b128 v[206:209], v197 offset:9168
	s_waitcnt lgkmcnt(4)
	v_mfma_f32_16x16x32_bf16 v[84:87], v[84:87], v[36:39], 0
	v_mfma_f32_16x16x32_bf16 v[84:87], v[88:91], v[40:43], v[84:87]
	v_mfma_f32_16x16x32_bf16 v[84:87], v[92:95], v[44:47], v[84:87]
	v_mfma_f32_16x16x32_bf16 v[104:107], v[96:99], v[48:51], v[84:87]
	s_nop 5
	ds_read_b128 v[84:87], v197 offset:17408
	ds_read_b128 v[88:91], v197 offset:17472
	ds_read_b128 v[92:95], v197 offset:17536
	ds_read_b128 v[96:99], v197 offset:17600
	s_waitcnt lgkmcnt(4)
	v_mfma_f32_16x16x32_bf16 v[100:103], v[100:103], v[36:39], 0
	v_mfma_f32_16x16x32_bf16 v[100:103], v[198:201], v[40:43], v[100:103]
	v_mfma_f32_16x16x32_bf16 v[100:103], v[202:205], v[44:47], v[100:103]
	v_mfma_f32_16x16x32_bf16 v[100:103], v[206:209], v[48:51], v[100:103]
	ds_read_b128 v[198:201], v197 offset:17680
	ds_read_b128 v[202:205], v197 offset:17744
	ds_read_b128 v[206:209], v197 offset:17808
	ds_read_b128 v[230:233], v197 offset:17872
	s_waitcnt lgkmcnt(4)
	v_mfma_f32_16x16x32_bf16 v[84:87], v[84:87], v[36:39], 0
	v_mfma_f32_16x16x32_bf16 v[84:87], v[88:91], v[40:43], v[84:87]
	v_mfma_f32_16x16x32_bf16 v[84:87], v[92:95], v[44:47], v[84:87]
	v_mfma_f32_16x16x32_bf16 v[96:99], v[96:99], v[48:51], v[84:87]
	s_nop 5
	ds_read_b128 v[84:87], v197 offset:26112
	ds_read_b128 v[88:91], v197 offset:26176
	ds_read_b128 v[234:237], v197 offset:26240
	ds_read_b128 v[238:241], v197 offset:26304
	s_waitcnt lgkmcnt(4)
	v_mfma_f32_16x16x32_bf16 v[92:95], v[198:201], v[36:39], 0
	v_mfma_f32_16x16x32_bf16 v[92:95], v[202:205], v[40:43], v[92:95]
	v_mfma_f32_16x16x32_bf16 v[92:95], v[206:209], v[44:47], v[92:95]
	v_mfma_f32_16x16x32_bf16 v[92:95], v[230:233], v[48:51], v[92:95]
	ds_read_b128 v[198:201], v197 offset:26384
	ds_read_b128 v[202:205], v197 offset:26448
	ds_read_b128 v[206:209], v197 offset:26512
	ds_read_b128 v[230:233], v197 offset:26576
	s_waitcnt lgkmcnt(4)
	v_mfma_f32_16x16x32_bf16 v[84:87], v[84:87], v[36:39], 0
	v_mfma_f32_16x16x32_bf16 v[84:87], v[88:91], v[40:43], v[84:87]
	v_mfma_f32_16x16x32_bf16 v[84:87], v[234:237], v[44:47], v[84:87]
	v_mfma_f32_16x16x32_bf16 v[88:91], v[238:241], v[48:51], v[84:87]
	s_waitcnt lgkmcnt(0)
	v_mfma_f32_16x16x32_bf16 v[84:87], v[198:201], v[36:39], 0
	v_mfma_f32_16x16x32_bf16 v[84:87], v[202:205], v[40:43], v[84:87]
	v_mfma_f32_16x16x32_bf16 v[84:87], v[206:209], v[44:47], v[84:87]
	v_mfma_f32_16x16x32_bf16 v[84:87], v[230:233], v[48:51], v[84:87]
	ds_read_b128 v[202:205], v195 offset:34816
	ds_read_b128 v[206:209], v195 offset:35088
	ds_read_b128 v[230:233], v195 offset:43520
	ds_read_b128 v[234:237], v195 offset:43792
	s_and_b64 vcc, exec, s[8:9]
	s_cbranch_vccnz .Lmb2_done
	s_xor_b32 s87, s15, 1
	s_mul_i32 s87, s87, 0x11000
	s_add_i32 s87, s87, 0
	v_add3_u32 v224, s87, v165, v216
	v_add3_u32 v223, s87, v0, v216
	v_add_u32_e32 v225, 0x8800, v224
	s_waitcnt vmcnt(7)
	ds_write_b128 v223, v[4:7]
	s_waitcnt vmcnt(6)
	ds_write2_b64 v225, v[8:9], v[10:11] offset1:2
	s_waitcnt vmcnt(5)
	ds_write_b128 v223, v[12:15] offset:8704
	v_add_u32_e32 v225, 0xa800, v224
	s_waitcnt vmcnt(4)
	ds_write2_b64 v225, v[16:17], v[18:19] offset0:64 offset1:66
	s_waitcnt vmcnt(3)
	ds_write_b128 v223, v[20:23] offset:17408
	v_add_u32_e32 v225, 0xc800, v224
	s_waitcnt vmcnt(2)
	ds_write2_b64 v225, v[24:25], v[26:27] offset0:128 offset1:130
	s_waitcnt vmcnt(1)
	ds_write_b128 v223, v[28:31] offset:26112
	v_add_u32_e32 v223, 0xe800, v224
	s_andn2_b64 vcc, exec, s[80:81]
	s_waitcnt vmcnt(0)
	ds_write2_b64 v223, v[32:33], v[34:35] offset0:192 offset1:194
	s_cbranch_vccnz .Lmb2_done
	s_lshr_b32 s82, s14, 1
	s_sub_i32 s82, s47, s82
	s_lshl_b32 s83, s14, 7
	s_lshl_b32 s82, s82, 8
	s_and_b32 s83, s83, 0x80
	s_or_b32 s82, s82, s83
	s_ashr_i32 s83, s82, 31
	v_lshl_add_u64 v[4:5], v[140:141], 0, s[82:83]
	v_mov_b64_e32 v[6:7], s[88:89]
	v_lshl_add_u64 v[28:29], s[82:83], 1, v[118:119]
	v_mad_u64_u32 v[6:7], s[82:83], v4, s72, v[6:7]
	v_mad_i32_i24 v7, v5, s72, v7
	v_lshl_add_u64 v[4:5], v[6:7], 0, s[20:21]
	v_lshl_add_u64 v[30:31], v[4:5], 0, v[2:3]
	v_add_co_u32_e32 v4, vcc, s3, v30
	s_mov_b32 s82, 0x3d000
	s_nop 0
	v_addc_co_u32_e32 v5, vcc, 0, v31, vcc
	v_add_co_u32_e32 v12, vcc, s82, v30
	v_lshl_add_u64 v[8:9], v[28:29], 0, v[146:147]
	s_nop 0
	v_addc_co_u32_e32 v13, vcc, 0, v31, vcc
	v_add_co_u32_e32 v20, vcc, 0x79000, v30
	v_lshl_add_u64 v[16:17], v[28:29], 0, v[148:149]
	s_nop 0
	v_addc_co_u32_e32 v21, vcc, 0, v31, vcc
	v_add_co_u32_e32 v30, vcc, 0xb5000, v30
	v_lshl_add_u64 v[24:25], v[28:29], 0, v[150:151]
	s_nop 0
	v_addc_co_u32_e32 v31, vcc, 0, v31, vcc
	v_lshl_add_u64 v[32:33], v[28:29], 0, v[152:153]
	global_load_dwordx4 v[4:7], v[4:5], off offset:1024
	s_nop 0
	global_load_dwordx4 v[8:11], v[8:9], off
	s_nop 0
	global_load_dwordx4 v[12:15], v[12:13], off offset:1024
	s_nop 0
	global_load_dwordx4 v[16:19], v[16:17], off
	s_nop 0
	global_load_dwordx4 v[20:23], v[20:21], off offset:1024
	s_nop 0
	global_load_dwordx4 v[24:27], v[24:25], off
	s_nop 0
	global_load_dwordx4 v[28:31], v[30:31], off offset:1024
	s_nop 0
	global_load_dwordx4 v[32:35], v[32:33], off
.Lmb2_done:
	v_and_b32_e32 v197, s0, v139
	v_cmp_eq_u32_e64 s[0:1], 0, v197
	s_cmp_lt_u32 s51, 2
	s_mov_b64 s[10:11], -1
	s_cbranch_scc1 .LBB0_154
	v_max3_f32 v197, v112, v113, v114
	v_max3_f32 v198, v96, v97, v98
	v_max3_f32 v197, v197, v115, v108
	v_max3_f32 v198, v198, v99, v92
	v_max3_f32 v197, v197, v109, v110
	v_max3_f32 v198, v198, v93, v94
	v_max3_f32 v197, v197, v111, v104
	v_max3_f32 v198, v198, v95, v88
	v_max3_f32 v197, v197, v105, v106
	v_max3_f32 v198, v198, v89, v90
	v_max3_f32 v197, v197, v107, v100
	v_max3_f32 v198, v198, v91, v84
	v_max3_f32 v197, v197, v101, v102
	v_max3_f32 v198, v198, v85, v86
	v_max_f32_e32 v197, v197, v103
	v_max_f32_e32 v198, v198, v87
	v_max_f32_e32 v197, v197, v198
	v_cndmask_b32_e64 v197, v197, v215, s[0:1]
	s_mov_b64 s[10:11], 0
